# GEMM f32 epilogue mode 0: stores cover whole 128-byte lines (lanes 8-15 of each row exchange with lanes 0-7 by DPP row_ror:8), was 64-byte half lines
# baseline (speedup 1.0000x reference)
; __device__ __forceinline__ void epilogue(const f32x4 (&acc)[2][2][4][2], const Unit& u, LAS unsigned char* lds, int wr, int wc, int fr, int fq) {
;     ...
;     if (mode == 0 || mode >= 5) {
;         float* C = (float*)Cp; const float* bias = (const float*)rfl_ptr(jobs[u.j].bias);
; #pragma unroll
;         for (int ai = 0; ai < 2; ++ai)
; #pragma unroll
;             for (int m = 0; m < 4; ++m) { float* rowp = C + (size_t)(row0 + ai * HALF + m * 16) * ldc + col0;
; #pragma unroll
;                 for (int bj = 0; bj < 2; ++bj)
; #pragma unroll
;                     for (int n = 0; n < 2; ++n) { f32x4 v = acc[ai][bj][m][n];
;                         if (mode >= 5) { v += *(const f32x4*)(bias + col0 + bj * HALF + n * 16);
; #pragma unroll
;                             for (int q = 0; q < 4; ++q) { const float sg = __builtin_amdgcn_rcpf(1.f + __expf(-v[q])); v[q] = mode == 5 ? __expf(-0.6065306597126334f * sg) : sg; } }
;                         *(f32x4*)(rowp + bj * HALF + n * 16) = v; }
;                 asm volatile("" ::: "memory"); }
.Lepi_f0:
	s_lshl_b64 s[98:99], s[26:27], 5
	s_sub_u32 s100, 64, s98
	s_subb_u32 s101, 0, s99
	s_lshl_b64 s[2:3], s[26:27], 6
	v_mbcnt_lo_u32_b32 v248, -1, 0
	v_mbcnt_hi_u32_b32 v248, -1, v248
	v_and_b32_e32 v248, 8, v248
	v_cmp_ne_u32_e32 vcc, 0, v248
	v_mov_b32_e32 v250, s100
	v_mov_b32_e32 v251, s101
	v_cndmask_b32_e32 v250, 0, v250, vcc
	v_cndmask_b32_e32 v251, 0, v251, vcc
	v_lshl_add_u64 v[144:145], v[144:145], 0, v[250:251]
	v_lshl_add_u64 v[142:143], v[144:145], 0, s[98:99]
	v_mov_b32_dpp v240, v124 row_ror:8 row_mask:0xf bank_mask:0xf
	v_mov_b32_dpp v241, v125 row_ror:8 row_mask:0xf bank_mask:0xf
	v_mov_b32_dpp v242, v126 row_ror:8 row_mask:0xf bank_mask:0xf
	v_mov_b32_dpp v243, v127 row_ror:8 row_mask:0xf bank_mask:0xf
	v_mov_b32_dpp v124, v128 row_ror:8 row_mask:0xf bank_mask:0x3
	v_mov_b32_dpp v125, v129 row_ror:8 row_mask:0xf bank_mask:0x3
	v_mov_b32_dpp v126, v130 row_ror:8 row_mask:0xf bank_mask:0x3
	v_mov_b32_dpp v127, v131 row_ror:8 row_mask:0xf bank_mask:0x3
	v_mov_b32_dpp v128, v240 quad_perm:[0,1,2,3] row_mask:0xf bank_mask:0xc
	v_mov_b32_dpp v129, v241 quad_perm:[0,1,2,3] row_mask:0xf bank_mask:0xc
	v_mov_b32_dpp v130, v242 quad_perm:[0,1,2,3] row_mask:0xf bank_mask:0xc
	v_mov_b32_dpp v131, v243 quad_perm:[0,1,2,3] row_mask:0xf bank_mask:0xc
	global_store_dwordx4 v[144:145], v[128:131], off
	global_store_dwordx4 v[142:143], v[124:127], off
	v_mov_b32_dpp v240, v116 row_ror:8 row_mask:0xf bank_mask:0xf
	v_mov_b32_dpp v241, v117 row_ror:8 row_mask:0xf bank_mask:0xf
	v_mov_b32_dpp v242, v118 row_ror:8 row_mask:0xf bank_mask:0xf
	v_mov_b32_dpp v243, v119 row_ror:8 row_mask:0xf bank_mask:0xf
	v_mov_b32_dpp v116, v120 row_ror:8 row_mask:0xf bank_mask:0x3
	v_mov_b32_dpp v117, v121 row_ror:8 row_mask:0xf bank_mask:0x3
	v_mov_b32_dpp v118, v122 row_ror:8 row_mask:0xf bank_mask:0x3
	v_mov_b32_dpp v119, v123 row_ror:8 row_mask:0xf bank_mask:0x3
	v_mov_b32_dpp v120, v240 quad_perm:[0,1,2,3] row_mask:0xf bank_mask:0xc
	v_mov_b32_dpp v121, v241 quad_perm:[0,1,2,3] row_mask:0xf bank_mask:0xc
	v_mov_b32_dpp v122, v242 quad_perm:[0,1,2,3] row_mask:0xf bank_mask:0xc
	v_mov_b32_dpp v123, v243 quad_perm:[0,1,2,3] row_mask:0xf bank_mask:0xc
	global_store_dwordx4 v[144:145], v[120:123], off offset:512
	global_store_dwordx4 v[142:143], v[116:119], off offset:512
	v_lshl_add_u64 v[144:145], s[2:3], 0, v[144:145]
	v_lshl_add_u64 v[142:143], s[2:3], 0, v[142:143]
	v_mov_b32_dpp v240, v108 row_ror:8 row_mask:0xf bank_mask:0xf
	v_mov_b32_dpp v241, v109 row_ror:8 row_mask:0xf bank_mask:0xf
	v_mov_b32_dpp v242, v110 row_ror:8 row_mask:0xf bank_mask:0xf
	v_mov_b32_dpp v243, v111 row_ror:8 row_mask:0xf bank_mask:0xf
	v_mov_b32_dpp v108, v112 row_ror:8 row_mask:0xf bank_mask:0x3
	v_mov_b32_dpp v109, v113 row_ror:8 row_mask:0xf bank_mask:0x3
	v_mov_b32_dpp v110, v114 row_ror:8 row_mask:0xf bank_mask:0x3
	v_mov_b32_dpp v111, v115 row_ror:8 row_mask:0xf bank_mask:0x3
	v_mov_b32_dpp v112, v240 quad_perm:[0,1,2,3] row_mask:0xf bank_mask:0xc
	v_mov_b32_dpp v113, v241 quad_perm:[0,1,2,3] row_mask:0xf bank_mask:0xc
	v_mov_b32_dpp v114, v242 quad_perm:[0,1,2,3] row_mask:0xf bank_mask:0xc
	v_mov_b32_dpp v115, v243 quad_perm:[0,1,2,3] row_mask:0xf bank_mask:0xc
	global_store_dwordx4 v[144:145], v[112:115], off
	global_store_dwordx4 v[142:143], v[108:111], off
	v_mov_b32_dpp v240, v100 row_ror:8 row_mask:0xf bank_mask:0xf
	v_mov_b32_dpp v241, v101 row_ror:8 row_mask:0xf bank_mask:0xf
	v_mov_b32_dpp v242, v102 row_ror:8 row_mask:0xf bank_mask:0xf
	v_mov_b32_dpp v243, v103 row_ror:8 row_mask:0xf bank_mask:0xf
	v_mov_b32_dpp v100, v104 row_ror:8 row_mask:0xf bank_mask:0x3
	v_mov_b32_dpp v101, v105 row_ror:8 row_mask:0xf bank_mask:0x3
	v_mov_b32_dpp v102, v106 row_ror:8 row_mask:0xf bank_mask:0x3
	v_mov_b32_dpp v103, v107 row_ror:8 row_mask:0xf bank_mask:0x3
	v_mov_b32_dpp v104, v240 quad_perm:[0,1,2,3] row_mask:0xf bank_mask:0xc
	v_mov_b32_dpp v105, v241 quad_perm:[0,1,2,3] row_mask:0xf bank_mask:0xc
	v_mov_b32_dpp v106, v242 quad_perm:[0,1,2,3] row_mask:0xf bank_mask:0xc
	v_mov_b32_dpp v107, v243 quad_perm:[0,1,2,3] row_mask:0xf bank_mask:0xc
	global_store_dwordx4 v[144:145], v[104:107], off offset:512
	global_store_dwordx4 v[142:143], v[100:103], off offset:512
	v_lshl_add_u64 v[144:145], s[2:3], 0, v[144:145]
	v_lshl_add_u64 v[142:143], s[2:3], 0, v[142:143]
	v_mov_b32_dpp v240, v92 row_ror:8 row_mask:0xf bank_mask:0xf
	v_mov_b32_dpp v241, v93 row_ror:8 row_mask:0xf bank_mask:0xf
	v_mov_b32_dpp v242, v94 row_ror:8 row_mask:0xf bank_mask:0xf
	v_mov_b32_dpp v243, v95 row_ror:8 row_mask:0xf bank_mask:0xf
	v_mov_b32_dpp v92, v96 row_ror:8 row_mask:0xf bank_mask:0x3
	v_mov_b32_dpp v93, v97 row_ror:8 row_mask:0xf bank_mask:0x3
	v_mov_b32_dpp v94, v98 row_ror:8 row_mask:0xf bank_mask:0x3
	v_mov_b32_dpp v95, v99 row_ror:8 row_mask:0xf bank_mask:0x3
	v_mov_b32_dpp v96, v240 quad_perm:[0,1,2,3] row_mask:0xf bank_mask:0xc
	v_mov_b32_dpp v97, v241 quad_perm:[0,1,2,3] row_mask:0xf bank_mask:0xc
	v_mov_b32_dpp v98, v242 quad_perm:[0,1,2,3] row_mask:0xf bank_mask:0xc
	v_mov_b32_dpp v99, v243 quad_perm:[0,1,2,3] row_mask:0xf bank_mask:0xc
	global_store_dwordx4 v[144:145], v[96:99], off
	global_store_dwordx4 v[142:143], v[92:95], off
	v_mov_b32_dpp v240, v84 row_ror:8 row_mask:0xf bank_mask:0xf
	v_mov_b32_dpp v241, v85 row_ror:8 row_mask:0xf bank_mask:0xf
	v_mov_b32_dpp v242, v86 row_ror:8 row_mask:0xf bank_mask:0xf
	v_mov_b32_dpp v243, v87 row_ror:8 row_mask:0xf bank_mask:0xf
	v_mov_b32_dpp v84, v88 row_ror:8 row_mask:0xf bank_mask:0x3
	v_mov_b32_dpp v85, v89 row_ror:8 row_mask:0xf bank_mask:0x3
	v_mov_b32_dpp v86, v90 row_ror:8 row_mask:0xf bank_mask:0x3
; __device__ __forceinline__ void epilogue(const f32x4 (&acc)[2][2][4][2], const Unit& u, LAS unsigned char* lds, int wr, int wc, int fr, int fq) {
;     ...
;     if (mode == 0 || mode >= 5) {
;         float* C = (float*)Cp; const float* bias = (const float*)rfl_ptr(jobs[u.j].bias);
; #pragma unroll
;         for (int ai = 0; ai < 2; ++ai)
; #pragma unroll
;             for (int m = 0; m < 4; ++m) { float* rowp = C + (size_t)(row0 + ai * HALF + m * 16) * ldc + col0;
; #pragma unroll
;                 for (int bj = 0; bj < 2; ++bj)
; #pragma unroll
;                     for (int n = 0; n < 2; ++n) { f32x4 v = acc[ai][bj][m][n];
;                         if (mode >= 5) { v += *(const f32x4*)(bias + col0 + bj * HALF + n * 16);
; #pragma unroll
;                             for (int q = 0; q < 4; ++q) { const float sg = __builtin_amdgcn_rcpf(1.f + __expf(-v[q])); v[q] = mode == 5 ? __expf(-0.6065306597126334f * sg) : sg; } }
;                         *(f32x4*)(rowp + bj * HALF + n * 16) = v; }
;                 asm volatile("" ::: "memory"); }
	v_mov_b32_dpp v87, v91 row_ror:8 row_mask:0xf bank_mask:0x3
	v_mov_b32_dpp v88, v240 quad_perm:[0,1,2,3] row_mask:0xf bank_mask:0xc
	v_mov_b32_dpp v89, v241 quad_perm:[0,1,2,3] row_mask:0xf bank_mask:0xc
	v_mov_b32_dpp v90, v242 quad_perm:[0,1,2,3] row_mask:0xf bank_mask:0xc
	v_mov_b32_dpp v91, v243 quad_perm:[0,1,2,3] row_mask:0xf bank_mask:0xc
	global_store_dwordx4 v[144:145], v[88:91], off offset:512
	global_store_dwordx4 v[142:143], v[84:87], off offset:512
	v_lshl_add_u64 v[144:145], s[2:3], 0, v[144:145]
	v_lshl_add_u64 v[142:143], s[2:3], 0, v[142:143]
	v_mov_b32_dpp v240, v76 row_ror:8 row_mask:0xf bank_mask:0xf
	v_mov_b32_dpp v241, v77 row_ror:8 row_mask:0xf bank_mask:0xf
	v_mov_b32_dpp v242, v78 row_ror:8 row_mask:0xf bank_mask:0xf
	v_mov_b32_dpp v243, v79 row_ror:8 row_mask:0xf bank_mask:0xf
	v_mov_b32_dpp v76, v80 row_ror:8 row_mask:0xf bank_mask:0x3
	v_mov_b32_dpp v77, v81 row_ror:8 row_mask:0xf bank_mask:0x3
	v_mov_b32_dpp v78, v82 row_ror:8 row_mask:0xf bank_mask:0x3
	v_mov_b32_dpp v79, v83 row_ror:8 row_mask:0xf bank_mask:0x3
	v_mov_b32_dpp v80, v240 quad_perm:[0,1,2,3] row_mask:0xf bank_mask:0xc
	v_mov_b32_dpp v81, v241 quad_perm:[0,1,2,3] row_mask:0xf bank_mask:0xc
	v_mov_b32_dpp v82, v242 quad_perm:[0,1,2,3] row_mask:0xf bank_mask:0xc
	v_mov_b32_dpp v83, v243 quad_perm:[0,1,2,3] row_mask:0xf bank_mask:0xc
	global_store_dwordx4 v[144:145], v[80:83], off
	global_store_dwordx4 v[142:143], v[76:79], off
	v_mov_b32_dpp v240, v68 row_ror:8 row_mask:0xf bank_mask:0xf
	v_mov_b32_dpp v241, v69 row_ror:8 row_mask:0xf bank_mask:0xf
	v_mov_b32_dpp v242, v70 row_ror:8 row_mask:0xf bank_mask:0xf
	v_mov_b32_dpp v243, v71 row_ror:8 row_mask:0xf bank_mask:0xf
	v_mov_b32_dpp v68, v72 row_ror:8 row_mask:0xf bank_mask:0x3
	v_mov_b32_dpp v69, v73 row_ror:8 row_mask:0xf bank_mask:0x3
	v_mov_b32_dpp v70, v74 row_ror:8 row_mask:0xf bank_mask:0x3
	v_mov_b32_dpp v71, v75 row_ror:8 row_mask:0xf bank_mask:0x3
	v_mov_b32_dpp v72, v240 quad_perm:[0,1,2,3] row_mask:0xf bank_mask:0xc
	v_mov_b32_dpp v73, v241 quad_perm:[0,1,2,3] row_mask:0xf bank_mask:0xc
	v_mov_b32_dpp v74, v242 quad_perm:[0,1,2,3] row_mask:0xf bank_mask:0xc
	v_mov_b32_dpp v75, v243 quad_perm:[0,1,2,3] row_mask:0xf bank_mask:0xc
	global_store_dwordx4 v[144:145], v[72:75], off offset:512
	global_store_dwordx4 v[142:143], v[68:71], off offset:512
	v_lshl_add_u64 v[144:145], s[2:3], 2, v[144:145]
	v_lshl_add_u64 v[142:143], s[2:3], 2, v[142:143]
	v_lshl_add_u64 v[144:145], s[2:3], 0, v[144:145]
	v_lshl_add_u64 v[142:143], s[2:3], 0, v[142:143]
	v_mov_b32_dpp v240, v60 row_ror:8 row_mask:0xf bank_mask:0xf
	v_mov_b32_dpp v241, v61 row_ror:8 row_mask:0xf bank_mask:0xf
	v_mov_b32_dpp v242, v62 row_ror:8 row_mask:0xf bank_mask:0xf
	v_mov_b32_dpp v243, v63 row_ror:8 row_mask:0xf bank_mask:0xf
	v_mov_b32_dpp v60, v64 row_ror:8 row_mask:0xf bank_mask:0x3
	v_mov_b32_dpp v61, v65 row_ror:8 row_mask:0xf bank_mask:0x3
	v_mov_b32_dpp v62, v66 row_ror:8 row_mask:0xf bank_mask:0x3
	v_mov_b32_dpp v63, v67 row_ror:8 row_mask:0xf bank_mask:0x3
	v_mov_b32_dpp v64, v240 quad_perm:[0,1,2,3] row_mask:0xf bank_mask:0xc
	v_mov_b32_dpp v65, v241 quad_perm:[0,1,2,3] row_mask:0xf bank_mask:0xc
	v_mov_b32_dpp v66, v242 quad_perm:[0,1,2,3] row_mask:0xf bank_mask:0xc
	v_mov_b32_dpp v67, v243 quad_perm:[0,1,2,3] row_mask:0xf bank_mask:0xc
	global_store_dwordx4 v[144:145], v[64:67], off
	global_store_dwordx4 v[142:143], v[60:63], off
	v_mov_b32_dpp v240, v52 row_ror:8 row_mask:0xf bank_mask:0xf
	v_mov_b32_dpp v241, v53 row_ror:8 row_mask:0xf bank_mask:0xf
	v_mov_b32_dpp v242, v54 row_ror:8 row_mask:0xf bank_mask:0xf
	v_mov_b32_dpp v243, v55 row_ror:8 row_mask:0xf bank_mask:0xf
	v_mov_b32_dpp v52, v56 row_ror:8 row_mask:0xf bank_mask:0x3
	v_mov_b32_dpp v53, v57 row_ror:8 row_mask:0xf bank_mask:0x3
	v_mov_b32_dpp v54, v58 row_ror:8 row_mask:0xf bank_mask:0x3
	v_mov_b32_dpp v55, v59 row_ror:8 row_mask:0xf bank_mask:0x3
	v_mov_b32_dpp v56, v240 quad_perm:[0,1,2,3] row_mask:0xf bank_mask:0xc
	v_mov_b32_dpp v57, v241 quad_perm:[0,1,2,3] row_mask:0xf bank_mask:0xc
	v_mov_b32_dpp v58, v242 quad_perm:[0,1,2,3] row_mask:0xf bank_mask:0xc
	v_mov_b32_dpp v59, v243 quad_perm:[0,1,2,3] row_mask:0xf bank_mask:0xc
	global_store_dwordx4 v[144:145], v[56:59], off offset:512
	global_store_dwordx4 v[142:143], v[52:55], off offset:512
	v_lshl_add_u64 v[144:145], s[2:3], 0, v[144:145]
	v_lshl_add_u64 v[142:143], s[2:3], 0, v[142:143]
	v_mov_b32_dpp v240, v44 row_ror:8 row_mask:0xf bank_mask:0xf
	v_mov_b32_dpp v241, v45 row_ror:8 row_mask:0xf bank_mask:0xf
	v_mov_b32_dpp v242, v46 row_ror:8 row_mask:0xf bank_mask:0xf
	v_mov_b32_dpp v243, v47 row_ror:8 row_mask:0xf bank_mask:0xf
	v_mov_b32_dpp v44, v48 row_ror:8 row_mask:0xf bank_mask:0x3
	v_mov_b32_dpp v45, v49 row_ror:8 row_mask:0xf bank_mask:0x3
	v_mov_b32_dpp v46, v50 row_ror:8 row_mask:0xf bank_mask:0x3
	v_mov_b32_dpp v47, v51 row_ror:8 row_mask:0xf bank_mask:0x3
	v_mov_b32_dpp v48, v240 quad_perm:[0,1,2,3] row_mask:0xf bank_mask:0xc
; __device__ __forceinline__ void epilogue(const f32x4 (&acc)[2][2][4][2], const Unit& u, LAS unsigned char* lds, int wr, int wc, int fr, int fq) {
;     ...
;     if (mode == 0 || mode >= 5) {
;         float* C = (float*)Cp; const float* bias = (const float*)rfl_ptr(jobs[u.j].bias);
; #pragma unroll
;         for (int ai = 0; ai < 2; ++ai)
; #pragma unroll
;             for (int m = 0; m < 4; ++m) { float* rowp = C + (size_t)(row0 + ai * HALF + m * 16) * ldc + col0;
; #pragma unroll
;                 for (int bj = 0; bj < 2; ++bj)
; #pragma unroll
;                     for (int n = 0; n < 2; ++n) { f32x4 v = acc[ai][bj][m][n];
;                         if (mode >= 5) { v += *(const f32x4*)(bias + col0 + bj * HALF + n * 16);
; #pragma unroll
;                             for (int q = 0; q < 4; ++q) { const float sg = __builtin_amdgcn_rcpf(1.f + __expf(-v[q])); v[q] = mode == 5 ? __expf(-0.6065306597126334f * sg) : sg; } }
;                         *(f32x4*)(rowp + bj * HALF + n * 16) = v; }
;                 asm volatile("" ::: "memory"); }
	v_mov_b32_dpp v49, v241 quad_perm:[0,1,2,3] row_mask:0xf bank_mask:0xc
	v_mov_b32_dpp v50, v242 quad_perm:[0,1,2,3] row_mask:0xf bank_mask:0xc
	v_mov_b32_dpp v51, v243 quad_perm:[0,1,2,3] row_mask:0xf bank_mask:0xc
	global_store_dwordx4 v[144:145], v[48:51], off
	global_store_dwordx4 v[142:143], v[44:47], off
	v_mov_b32_dpp v240, v36 row_ror:8 row_mask:0xf bank_mask:0xf
	v_mov_b32_dpp v241, v37 row_ror:8 row_mask:0xf bank_mask:0xf
	v_mov_b32_dpp v242, v38 row_ror:8 row_mask:0xf bank_mask:0xf
	v_mov_b32_dpp v243, v39 row_ror:8 row_mask:0xf bank_mask:0xf
	v_mov_b32_dpp v36, v40 row_ror:8 row_mask:0xf bank_mask:0x3
	v_mov_b32_dpp v37, v41 row_ror:8 row_mask:0xf bank_mask:0x3
	v_mov_b32_dpp v38, v42 row_ror:8 row_mask:0xf bank_mask:0x3
	v_mov_b32_dpp v39, v43 row_ror:8 row_mask:0xf bank_mask:0x3
	v_mov_b32_dpp v40, v240 quad_perm:[0,1,2,3] row_mask:0xf bank_mask:0xc
	v_mov_b32_dpp v41, v241 quad_perm:[0,1,2,3] row_mask:0xf bank_mask:0xc
	v_mov_b32_dpp v42, v242 quad_perm:[0,1,2,3] row_mask:0xf bank_mask:0xc
	v_mov_b32_dpp v43, v243 quad_perm:[0,1,2,3] row_mask:0xf bank_mask:0xc
	global_store_dwordx4 v[144:145], v[40:43], off offset:512
	global_store_dwordx4 v[142:143], v[36:39], off offset:512
	v_lshl_add_u64 v[144:145], s[2:3], 0, v[144:145]
	v_lshl_add_u64 v[142:143], s[2:3], 0, v[142:143]
	v_mov_b32_dpp v240, v28 row_ror:8 row_mask:0xf bank_mask:0xf
	v_mov_b32_dpp v241, v29 row_ror:8 row_mask:0xf bank_mask:0xf
	v_mov_b32_dpp v242, v30 row_ror:8 row_mask:0xf bank_mask:0xf
	v_mov_b32_dpp v243, v31 row_ror:8 row_mask:0xf bank_mask:0xf
	v_mov_b32_dpp v28, v32 row_ror:8 row_mask:0xf bank_mask:0x3
	v_mov_b32_dpp v29, v33 row_ror:8 row_mask:0xf bank_mask:0x3
	v_mov_b32_dpp v30, v34 row_ror:8 row_mask:0xf bank_mask:0x3
	v_mov_b32_dpp v31, v35 row_ror:8 row_mask:0xf bank_mask:0x3
	v_mov_b32_dpp v32, v240 quad_perm:[0,1,2,3] row_mask:0xf bank_mask:0xc
	v_mov_b32_dpp v33, v241 quad_perm:[0,1,2,3] row_mask:0xf bank_mask:0xc
	v_mov_b32_dpp v34, v242 quad_perm:[0,1,2,3] row_mask:0xf bank_mask:0xc
	v_mov_b32_dpp v35, v243 quad_perm:[0,1,2,3] row_mask:0xf bank_mask:0xc
	global_store_dwordx4 v[144:145], v[32:35], off
	global_store_dwordx4 v[142:143], v[28:31], off
	v_mov_b32_dpp v240, v20 row_ror:8 row_mask:0xf bank_mask:0xf
	v_mov_b32_dpp v241, v21 row_ror:8 row_mask:0xf bank_mask:0xf
	v_mov_b32_dpp v242, v22 row_ror:8 row_mask:0xf bank_mask:0xf
	v_mov_b32_dpp v243, v23 row_ror:8 row_mask:0xf bank_mask:0xf
	v_mov_b32_dpp v20, v24 row_ror:8 row_mask:0xf bank_mask:0x3
	v_mov_b32_dpp v21, v25 row_ror:8 row_mask:0xf bank_mask:0x3
	v_mov_b32_dpp v22, v26 row_ror:8 row_mask:0xf bank_mask:0x3
	v_mov_b32_dpp v23, v27 row_ror:8 row_mask:0xf bank_mask:0x3
	v_mov_b32_dpp v24, v240 quad_perm:[0,1,2,3] row_mask:0xf bank_mask:0xc
	v_mov_b32_dpp v25, v241 quad_perm:[0,1,2,3] row_mask:0xf bank_mask:0xc
	v_mov_b32_dpp v26, v242 quad_perm:[0,1,2,3] row_mask:0xf bank_mask:0xc
	v_mov_b32_dpp v27, v243 quad_perm:[0,1,2,3] row_mask:0xf bank_mask:0xc
	global_store_dwordx4 v[144:145], v[24:27], off offset:512
	global_store_dwordx4 v[142:143], v[20:23], off offset:512
	v_lshl_add_u64 v[144:145], s[2:3], 0, v[144:145]
	v_lshl_add_u64 v[142:143], s[2:3], 0, v[142:143]
	v_mov_b32_dpp v240, v12 row_ror:8 row_mask:0xf bank_mask:0xf
	v_mov_b32_dpp v241, v13 row_ror:8 row_mask:0xf bank_mask:0xf
	v_mov_b32_dpp v242, v14 row_ror:8 row_mask:0xf bank_mask:0xf
	v_mov_b32_dpp v243, v15 row_ror:8 row_mask:0xf bank_mask:0xf
	v_mov_b32_dpp v12, v16 row_ror:8 row_mask:0xf bank_mask:0x3
	v_mov_b32_dpp v13, v17 row_ror:8 row_mask:0xf bank_mask:0x3
	v_mov_b32_dpp v14, v18 row_ror:8 row_mask:0xf bank_mask:0x3
	v_mov_b32_dpp v15, v19 row_ror:8 row_mask:0xf bank_mask:0x3
	v_mov_b32_dpp v16, v240 quad_perm:[0,1,2,3] row_mask:0xf bank_mask:0xc
	v_mov_b32_dpp v17, v241 quad_perm:[0,1,2,3] row_mask:0xf bank_mask:0xc
	v_mov_b32_dpp v18, v242 quad_perm:[0,1,2,3] row_mask:0xf bank_mask:0xc
	v_mov_b32_dpp v19, v243 quad_perm:[0,1,2,3] row_mask:0xf bank_mask:0xc
	global_store_dwordx4 v[144:145], v[16:19], off
	global_store_dwordx4 v[142:143], v[12:15], off
	v_mov_b32_dpp v240, v4 row_ror:8 row_mask:0xf bank_mask:0xf
	v_mov_b32_dpp v241, v5 row_ror:8 row_mask:0xf bank_mask:0xf
	v_mov_b32_dpp v242, v6 row_ror:8 row_mask:0xf bank_mask:0xf
	v_mov_b32_dpp v243, v7 row_ror:8 row_mask:0xf bank_mask:0xf
	v_mov_b32_dpp v4, v8 row_ror:8 row_mask:0xf bank_mask:0x3
	v_mov_b32_dpp v5, v9 row_ror:8 row_mask:0xf bank_mask:0x3
	v_mov_b32_dpp v6, v10 row_ror:8 row_mask:0xf bank_mask:0x3
	v_mov_b32_dpp v7, v11 row_ror:8 row_mask:0xf bank_mask:0x3
	v_mov_b32_dpp v8, v240 quad_perm:[0,1,2,3] row_mask:0xf bank_mask:0xc
	v_mov_b32_dpp v9, v241 quad_perm:[0,1,2,3] row_mask:0xf bank_mask:0xc
	v_mov_b32_dpp v10, v242 quad_perm:[0,1,2,3] row_mask:0xf bank_mask:0xc
	v_mov_b32_dpp v11, v243 quad_perm:[0,1,2,3] row_mask:0xf bank_mask:0xc
	global_store_dwordx4 v[144:145], v[8:11], off offset:512
	global_store_dwordx4 v[142:143], v[4:7], off offset:512
	s_branch .LBB0_1310
